# XCD barrier: non-leader workgroups poll the cross-XCD generation word directly (skips the per-XCD release hop)
# speedup vs baseline: 1.0202x; 1.0031x over previous
.Ls0b_396:
	v_readlane_b32 s4, v249, 20
	s_lshl_b32 s4, s4, 8
	v_readlane_b32 s6, v249, 18
	v_readlane_b32 s7, v249, 19
	s_add_u32 s4, s6, s4
	s_addc_u32 s5, s7, 0
	v_mov_b32_e32 v1, 0x1000
	v_mov_b32_e32 v3, 1
	global_atomic_add v3, v1, v3, s[4:5] offset:1024 sc0
	v_cvt_f32_u32_e32 v1, v2
	v_sub_u32_e32 v4, 0, v2
	v_rcp_iflag_f32_e32 v1, v1
	s_nop 0
	v_mul_f32_e32 v1, 0x4f7ffffe, v1
	v_cvt_u32_f32_e32 v1, v1
	v_mul_lo_u32 v4, v4, v1
	v_mul_hi_u32 v4, v1, v4
	v_add_u32_e32 v1, v1, v4
	s_waitcnt vmcnt(0)
	v_mul_hi_u32 v1, v3, v1
	v_mul_lo_u32 v4, v1, v2
	v_sub_u32_e32 v4, v3, v4
	v_add_u32_e32 v5, 1, v1
	v_cmp_ge_u32_e32 vcc, v4, v2
	v_add_u32_e32 v3, 1, v3
	s_nop 0
	v_cndmask_b32_e32 v1, v1, v5, vcc
	v_sub_u32_e32 v5, v4, v2
	v_cndmask_b32_e32 v4, v4, v5, vcc
	v_add_u32_e32 v5, 1, v1
	v_cmp_ge_u32_e32 vcc, v4, v2
	s_nop 1
	v_cndmask_b32_e32 v1, v1, v5, vcc
	v_mul_lo_u32 v4, v2, v1
	v_add_u32_e32 v2, v4, v2
	v_cmp_ne_u32_e32 vcc, v3, v2
	s_and_saveexec_b64 s[6:7], vcc
	s_xor_b64 s[6:7], exec, s[6:7]
	s_cbranch_execz .Ls0b_410
	s_waitcnt lgkmcnt(0)
	s_add_u32 s12, s30, 0x313500
	s_addc_u32 s13, s31, 0
	v_mov_b32_e32 v0, 0
	global_load_dword v0, v0, s[12:13] sc1
	s_waitcnt vmcnt(0)
	v_cmp_eq_u32_e32 vcc, v0, v1
	s_and_saveexec_b64 s[8:9], vcc
	s_cbranch_execz .Ls0b_409
	s_add_u32 s10, s30, 0x310200
	s_addc_u32 s11, s31, 0
	s_mov_b32 s24, 1
	s_mov_b64 s[14:15], 0
	v_mov_b32_e32 v0, 0
	s_branch .Ls0b_400

.LBB0_929:
	v_readlane_b32 s2, v249, 20
	s_lshl_b32 s2, s2, 8
	v_readlane_b32 s4, v249, 18
	v_readlane_b32 s5, v249, 19
	s_add_u32 s2, s4, s2
	s_addc_u32 s3, s5, 0
	v_mov_b32_e32 v1, 0x1000
	v_mov_b32_e32 v3, 1
	global_atomic_add v3, v1, v3, s[2:3] offset:1024 sc0
	v_cvt_f32_u32_e32 v1, v2
	v_sub_u32_e32 v4, 0, v2
	v_rcp_iflag_f32_e32 v1, v1
	s_nop 0
	v_mul_f32_e32 v1, 0x4f7ffffe, v1
	v_cvt_u32_f32_e32 v1, v1
	v_mul_lo_u32 v4, v4, v1
	v_mul_hi_u32 v4, v1, v4
	v_add_u32_e32 v1, v1, v4
	s_waitcnt vmcnt(0)
	v_mul_hi_u32 v1, v3, v1
	v_mul_lo_u32 v4, v1, v2
	v_sub_u32_e32 v4, v3, v4
	v_add_u32_e32 v5, 1, v1
	v_cmp_ge_u32_e32 vcc, v4, v2
	v_add_u32_e32 v3, 1, v3
	s_nop 0
	v_cndmask_b32_e32 v1, v1, v5, vcc
	v_sub_u32_e32 v5, v4, v2
	v_cndmask_b32_e32 v4, v4, v5, vcc
	v_add_u32_e32 v5, 1, v1
	v_cmp_ge_u32_e32 vcc, v4, v2
	s_nop 1
	v_cndmask_b32_e32 v1, v1, v5, vcc
	v_mul_lo_u32 v4, v2, v1
	v_add_u32_e32 v2, v4, v2
	v_cmp_ne_u32_e32 vcc, v3, v2
	s_and_saveexec_b64 s[4:5], vcc
	s_xor_b64 s[4:5], exec, s[4:5]
	s_cbranch_execz .LBB0_943
	s_waitcnt lgkmcnt(0)
	s_add_u32 s10, s30, 0x313500
	s_addc_u32 s11, s31, 0
	v_mov_b32_e32 v0, 0
	global_load_dword v0, v0, s[10:11] sc1
	s_waitcnt vmcnt(0)
	v_cmp_eq_u32_e32 vcc, v0, v1
	s_and_saveexec_b64 s[6:7], vcc
	s_cbranch_execz .LBB0_942
	s_add_u32 s8, s30, 0x310200
	s_addc_u32 s9, s31, 0
	s_mov_b32 s22, 1
	s_mov_b64 s[12:13], 0
	v_mov_b32_e32 v0, 0
	s_branch .LBB0_933
